# code placement (9.3): 64-byte alignment of the nine hot loop heads (five GEMM main loops, selection, compressed pass 1/2, window)
# speedup vs baseline: 1.0072x; 1.0072x over previous
; template <class Epi>
; __device__ __forceinline__ void gemm_phase(LAS unsigned char* lds, const Gemm g, const StaticOrder& S, const Epi& E) {
;     ...
;         const bool has_next = S.next(ui + 1, nxt);
;         const char* nA = has_next ? (const char*)g.A + (size_t)nxt.pm * tA : cA; const char* nB = has_next ? (const char*)g.Bt + (size_t)nxt.pn * tB : cB;
;         for (int t = 0; t < nt; t += 2) {
;     ...
; #pragma unroll
;         for (int a = 0; a < 2; ++a)
; #pragma unroll
;             for (int b = 0; b < 2; ++b)
; #pragma unroll
;                 for (int m = 0; m < 4; ++m)
; #pragma unroll
;                     for (int n = 0; n < 2; ++n) acc[a][b][m][n] = (f32x4){0.f, 0.f, 0.f, 0.f};
;         cur = nxt; cA = nA; cB = nB; ++ui;
.LBB0_131:
	s_ashr_i32 s27, s26, 31
	s_lshl_b64 s[28:29], s[26:27], 19
	s_add_u32 s28, s54, s28
	s_addc_u32 s29, s55, s29
	s_and_b64 s[30:31], s[36:37], exec
	s_cselect_b32 s7, s29, s9
	s_cselect_b32 s27, s28, s8
	s_ashr_i32 s25, s24, 31
	s_lshl_b64 s[30:31], s[24:25], 19
	s_add_u32 s30, s52, s30
	s_addc_u32 s31, s53, s31
	s_and_b64 s[36:37], s[36:37], exec
	s_cselect_b32 s25, s31, s35
	s_cselect_b32 s38, s30, s34
	s_add_u32 s8, s8, 0x40080
	s_addc_u32 s9, s9, 0
	s_add_u32 s39, s34, 0x100
	v_mov_b64_e32 v[2:3], 0
	v_mov_b64_e32 v[4:5], 0
	v_mov_b64_e32 v[6:7], 0
	v_mov_b64_e32 v[8:9], 0
	v_mov_b64_e32 v[10:11], 0
	v_mov_b64_e32 v[12:13], 0
	v_mov_b64_e32 v[14:15], 0
	v_mov_b64_e32 v[16:17], 0
	v_mov_b64_e32 v[18:19], 0
	v_mov_b64_e32 v[20:21], 0
	v_mov_b64_e32 v[22:23], 0
	v_mov_b64_e32 v[24:25], 0
	v_mov_b64_e32 v[26:27], 0
	v_mov_b64_e32 v[28:29], 0
	v_mov_b64_e32 v[30:31], 0
	v_mov_b64_e32 v[32:33], 0
	v_mov_b64_e32 v[34:35], 0
	v_mov_b64_e32 v[36:37], 0
	v_mov_b64_e32 v[38:39], 0
	v_mov_b64_e32 v[40:41], 0
	v_mov_b64_e32 v[42:43], 0
	v_mov_b64_e32 v[44:45], 0
	v_mov_b64_e32 v[46:47], 0
	v_mov_b64_e32 v[48:49], 0
	v_mov_b64_e32 v[50:51], 0
	v_mov_b64_e32 v[52:53], 0
	v_mov_b64_e32 v[54:55], 0
	v_mov_b64_e32 v[56:57], 0
	v_mov_b64_e32 v[58:59], 0
	v_mov_b64_e32 v[60:61], 0
	v_mov_b64_e32 v[62:63], 0
	v_mov_b64_e32 v[64:65], 0
	v_mov_b64_e32 v[66:67], 0
	v_mov_b64_e32 v[68:69], 0
	v_mov_b64_e32 v[70:71], 0
	v_mov_b64_e32 v[72:73], 0
	v_mov_b64_e32 v[74:75], 0
	v_mov_b64_e32 v[76:77], 0
	v_mov_b64_e32 v[78:79], 0
	v_mov_b64_e32 v[80:81], 0
	v_mov_b64_e32 v[82:83], 0
	v_mov_b64_e32 v[84:85], 0
	v_mov_b64_e32 v[86:87], 0
	v_mov_b64_e32 v[88:89], 0
	v_mov_b64_e32 v[90:91], 0
	v_mov_b64_e32 v[92:93], 0
	v_mov_b64_e32 v[94:95], 0
	v_mov_b64_e32 v[96:97], 0
	v_mov_b64_e32 v[98:99], 0
	v_mov_b64_e32 v[100:101], 0
	v_mov_b64_e32 v[102:103], 0
	v_mov_b64_e32 v[104:105], 0
	v_mov_b64_e32 v[106:107], 0
	v_mov_b64_e32 v[108:109], 0
	v_mov_b64_e32 v[110:111], 0
	v_mov_b64_e32 v[112:113], 0
	v_mov_b64_e32 v[114:115], 0
	v_mov_b64_e32 v[116:117], 0
	v_mov_b64_e32 v[118:119], 0
	v_mov_b64_e32 v[120:121], 0
	v_mov_b64_e32 v[122:123], 0
	v_mov_b64_e32 v[124:125], 0
	v_mov_b64_e32 v[126:127], 0
	v_mov_b64_e32 v[128:129], 0
	s_addc_u32 s40, s35, 0
	s_mov_b32 s41, -2
	.p2align 6

; template <class Epi>
; __device__ __forceinline__ void gemm_phase(LAS unsigned char* lds, const Gemm g, const StaticOrder& S, const Epi& E) {
;     ...
;         const bool has_next = S.next(ui + 1, nxt);
;         const char* nA = has_next ? (const char*)g.A + (size_t)nxt.pm * tA : cA; const char* nB = has_next ? (const char*)g.Bt + (size_t)nxt.pn * tB : cB;
;         for (int t = 0; t < nt; t += 2) {
;     ...
; #pragma unroll
;         for (int a = 0; a < 2; ++a)
; #pragma unroll
;             for (int b = 0; b < 2; ++b)
; #pragma unroll
;                 for (int m = 0; m < 4; ++m)
; #pragma unroll
;                     for (int n = 0; n < 2; ++n) acc[a][b][m][n] = (f32x4){0.f, 0.f, 0.f, 0.f};
;         cur = nxt; cA = nA; cB = nB; ++ui;
.LBB0_517:
	s_ashr_i32 s21, s20, 31
	s_lshl_b64 s[22:23], s[20:21], 19
	s_add_u32 s22, s51, s22
	s_addc_u32 s23, s52, s23
	s_and_b64 s[24:25], s[34:35], exec
	s_cselect_b32 s21, s23, s29
	s_cselect_b32 s27, s22, s28
	s_ashr_i32 s19, s18, 31
	s_lshl_b64 s[24:25], s[18:19], 20
	s_add_u32 s24, s12, s24
	s_addc_u32 s25, s13, s25
	s_and_b64 s[34:35], s[34:35], exec
	s_cselect_b32 s19, s25, s31
	s_cselect_b32 s65, s24, s30
	s_add_u32 s28, s28, 0x40080
	s_addc_u32 s29, s29, 0
	s_add_u32 s66, s30, 0x100
	v_mov_b32_e32 v2, 0
	s_addc_u32 s67, s31, 0
	s_mov_b32 s70, -2
	v_mov_b32_e32 v3, v2
	v_mov_b32_e32 v4, v2
	v_mov_b32_e32 v5, v2
	v_mov_b32_e32 v6, v2
	v_mov_b32_e32 v7, v2
	v_mov_b32_e32 v8, v2
	v_mov_b32_e32 v9, v2
	v_mov_b32_e32 v10, v2
	v_mov_b32_e32 v11, v2
	v_mov_b32_e32 v12, v2
	v_mov_b32_e32 v13, v2
	v_mov_b32_e32 v14, v2
	v_mov_b32_e32 v15, v2
	v_mov_b32_e32 v16, v2
	v_mov_b32_e32 v17, v2
	v_mov_b32_e32 v18, v2
	v_mov_b32_e32 v19, v2
	v_mov_b32_e32 v20, v2
	v_mov_b32_e32 v21, v2
	v_mov_b32_e32 v22, v2
	v_mov_b32_e32 v23, v2
	v_mov_b32_e32 v24, v2
	v_mov_b32_e32 v25, v2
	v_mov_b32_e32 v26, v2
	v_mov_b32_e32 v27, v2
	v_mov_b32_e32 v28, v2
	v_mov_b32_e32 v29, v2
	v_mov_b32_e32 v30, v2
	v_mov_b32_e32 v31, v2
	v_mov_b32_e32 v32, v2
	v_mov_b32_e32 v33, v2
	v_mov_b32_e32 v66, v2
	v_mov_b32_e32 v67, v2
	v_mov_b32_e32 v68, v2
	v_mov_b32_e32 v69, v2
	v_mov_b32_e32 v70, v2
	v_mov_b32_e32 v71, v2
	v_mov_b32_e32 v72, v2
	v_mov_b32_e32 v73, v2
	v_mov_b32_e32 v74, v2
	v_mov_b32_e32 v75, v2
	v_mov_b32_e32 v76, v2
	v_mov_b32_e32 v77, v2
	v_mov_b32_e32 v78, v2
	v_mov_b32_e32 v79, v2
	v_mov_b32_e32 v80, v2
	v_mov_b32_e32 v81, v2
	v_mov_b32_e32 v82, v2
	v_mov_b32_e32 v83, v2
	v_mov_b32_e32 v84, v2
	v_mov_b32_e32 v85, v2
	v_mov_b32_e32 v86, v2
	v_mov_b32_e32 v87, v2
	v_mov_b32_e32 v88, v2
	v_mov_b32_e32 v89, v2
	v_mov_b32_e32 v90, v2
	v_mov_b32_e32 v91, v2
	v_mov_b32_e32 v92, v2
	v_mov_b32_e32 v93, v2
	v_mov_b32_e32 v94, v2
	v_mov_b32_e32 v95, v2
	v_mov_b32_e32 v96, v2
	v_mov_b32_e32 v97, v2
	v_mov_b32_e32 v34, v2
	v_mov_b32_e32 v35, v2
	v_mov_b32_e32 v36, v2
	v_mov_b32_e32 v37, v2
	v_mov_b32_e32 v38, v2
	v_mov_b32_e32 v39, v2
	v_mov_b32_e32 v40, v2
	v_mov_b32_e32 v41, v2
	v_mov_b32_e32 v42, v2
	v_mov_b32_e32 v43, v2
	v_mov_b32_e32 v44, v2
	v_mov_b32_e32 v45, v2
	v_mov_b32_e32 v46, v2
	v_mov_b32_e32 v47, v2
	v_mov_b32_e32 v48, v2
	v_mov_b32_e32 v49, v2
	v_mov_b32_e32 v50, v2
	v_mov_b32_e32 v51, v2
	v_mov_b32_e32 v52, v2
	v_mov_b32_e32 v53, v2
	v_mov_b32_e32 v54, v2
	v_mov_b32_e32 v55, v2
	v_mov_b32_e32 v56, v2
	v_mov_b32_e32 v57, v2
	v_mov_b32_e32 v58, v2
	v_mov_b32_e32 v59, v2
	v_mov_b32_e32 v60, v2
	v_mov_b32_e32 v61, v2
	v_mov_b32_e32 v62, v2
	v_mov_b32_e32 v63, v2
	v_mov_b32_e32 v64, v2
	v_mov_b32_e32 v65, v2
	v_mov_b32_e32 v106, v2
	v_mov_b32_e32 v107, v2
	v_mov_b32_e32 v108, v2
	v_mov_b32_e32 v109, v2
	v_mov_b32_e32 v110, v2
	v_mov_b32_e32 v111, v2
	v_mov_b32_e32 v112, v2
	v_mov_b32_e32 v113, v2
	v_mov_b32_e32 v114, v2
	v_mov_b32_e32 v115, v2
	v_mov_b32_e32 v116, v2
	v_mov_b32_e32 v117, v2
	v_mov_b32_e32 v118, v2
	v_mov_b32_e32 v119, v2
	v_mov_b32_e32 v120, v2
	v_mov_b32_e32 v121, v2
	v_mov_b32_e32 v122, v2
	v_mov_b32_e32 v123, v2
	v_mov_b32_e32 v124, v2
	v_mov_b32_e32 v125, v2
	v_mov_b32_e32 v126, v2
	v_mov_b32_e32 v127, v2
	v_mov_b32_e32 v128, v2
	v_mov_b32_e32 v129, v2
	v_mov_b32_e32 v130, v2
	v_mov_b32_e32 v131, v2
	v_mov_b32_e32 v132, v2
	v_mov_b32_e32 v133, v2
	v_mov_b32_e32 v134, v2
	v_mov_b32_e32 v135, v2
	v_mov_b32_e32 v136, v2
	v_mov_b32_e32 v137, v2
	.p2align 6

; __device__ __forceinline__ void nsa_unit(const Params& p, int bg, int jq, LAS unsigned char* lds, int wave, int lane, bool build_lut) {
;     ...
;         for (int T = 0; T < ntile; ++T) {
; #pragma unroll
;             for (int ks = 0; ks < 4; ++ks) kf[ks] = kn[ks];
;             if (T + 1 < ntile) load_k(kn, kcmp + (size_t)(T + 1) * 2048, lane);
.LBB0_1053:
	v_mov_b32_e32 v84, v85
	v_mov_b32_e32 v83, v86
	s_waitcnt vmcnt(0)
	.p2align 6

; __device__ __forceinline__ void nsa_unit(const Params& p, int bg, int jq, LAS unsigned char* lds, int wave, int lane, bool build_lut) {
;     ...
;         const float c2 = (l > 0.f) ? (m + __builtin_amdgcn_logf(l)) : __builtin_inff();
;         const float c2f = c2 - lutfar;
;         f32x16 o0, o1;
; #pragma unroll
;         for (int i = 0; i < 16; ++i) { o0[i] = 0.f; o1[i] = 0.f; }
;         if (ntile > 0) load_k(kn, kcmp, lane);
;         for (int T = 0; T < ntile; ++T) {
; #pragma unroll
;             for (int ks = 0; ks < 4; ++ks) kf[ks] = kn[ks];
.LBB0_1093:
	v_mov_b32_e32 v17, 0
	s_and_b64 vcc, s[8:9], exec
	v_mov_b32_e32 v16, v17
	v_mov_b32_e32 v15, v17
	v_mov_b32_e32 v14, v17
	v_mov_b32_e32 v13, v17
	v_mov_b32_e32 v12, v17
	v_mov_b32_e32 v11, v17
	v_mov_b32_e32 v10, v17
	v_mov_b32_e32 v9, v17
	v_mov_b32_e32 v8, v17
	v_mov_b32_e32 v7, v17
	v_mov_b32_e32 v6, v17
	v_mov_b32_e32 v5, v17
	v_mov_b32_e32 v4, v17
	v_mov_b32_e32 v3, v17
	v_mov_b32_e32 v2, v17
	v_mov_b32_e32 v33, v17
	v_mov_b32_e32 v32, v17
	v_mov_b32_e32 v31, v17
	v_mov_b32_e32 v30, v17
	v_mov_b32_e32 v29, v17
	v_mov_b32_e32 v28, v17
	v_mov_b32_e32 v27, v17
	v_mov_b32_e32 v26, v17
	v_mov_b32_e32 v25, v17
	v_mov_b32_e32 v24, v17
	v_mov_b32_e32 v23, v17
	v_mov_b32_e32 v22, v17
	v_mov_b32_e32 v21, v17
	v_mov_b32_e32 v20, v17
	v_mov_b32_e32 v19, v17
	v_mov_b32_e32 v18, v17
	s_cbranch_vccz .LBB0_1147
	v_lshlrev_b32_e32 v4, 3, v145
	v_ashrrev_i32_e32 v5, 31, v4
	v_lshlrev_b64 v[4:5], 1, v[4:5]
	v_lshl_add_u64 v[6:7], s[6:7], 0, v[4:5]
	global_load_dwordx4 v[34:37], v[6:7], off
	global_load_dwordx4 v[50:53], v[6:7], off offset:1024
	global_load_dwordx4 v[54:57], v[6:7], off offset:2048
	global_load_dwordx4 v[58:61], v[6:7], off offset:3072
	s_lshl_b32 s19, s29, 6
	v_log_f32_e32 v3, v86
	s_add_i32 s19, s28, s19
	s_add_i32 s22, s19, s30
	s_sub_i32 s22, s22, 24
	s_lshr_b32 s22, s22, 9
	v_lshl_add_u32 v6, v158, 10, s18
	s_sub_i32 s23, s19, 31
	v_readlane_b32 s18, v253, 53
	v_cmp_lt_f32_e32 vcc, 0, v86
	v_add_f32_e32 v3, v85, v3
	v_lshlrev_b32_e32 v7, 2, v179
	s_add_u32 s18, s14, s18
	v_mov_b32_e32 v2, 0
	v_cndmask_b32_e32 v119, v229, v3, vcc
	v_lshlrev_b32_e32 v3, 6, v179
	v_add3_u32 v121, v6, v7, 0
	v_add_u32_e32 v6, s19, v158
	s_addc_u32 s19, s15, 0
	s_waitcnt lgkmcnt(0)
	v_sub_f32_e32 v120, v119, v184
	v_cmp_eq_u32_e64 s[6:7], 0, v1
	v_cmp_eq_u32_e64 s[8:9], 1, v1
	v_cmp_eq_u32_e64 s[10:11], 2, v1
	v_cmp_eq_u32_e64 s[12:13], 3, v1
	v_sub_u32_e32 v122, v6, v3
	v_lshl_add_u64 v[116:117], s[18:19], 0, v[4:5]
	s_mov_b32 s24, -1
	v_mov_b32_e32 v123, v179
	v_mov_b32_e32 v3, v2
	v_mov_b32_e32 v4, v2
	v_mov_b32_e32 v5, v2
	v_mov_b32_e32 v6, v2
	v_mov_b32_e32 v7, v2
	v_mov_b32_e32 v8, v2
	v_mov_b32_e32 v9, v2
	v_mov_b32_e32 v10, v2
	v_mov_b32_e32 v11, v2
	v_mov_b32_e32 v12, v2
	v_mov_b32_e32 v13, v2
	v_mov_b32_e32 v14, v2
	v_mov_b32_e32 v15, v2
	v_mov_b32_e32 v16, v2
	v_mov_b32_e32 v17, v2
	v_mov_b32_e32 v18, v2
	v_mov_b32_e32 v19, v2
	v_mov_b32_e32 v20, v2
	v_mov_b32_e32 v21, v2
	v_mov_b32_e32 v22, v2
	v_mov_b32_e32 v23, v2
	v_mov_b32_e32 v24, v2
	v_mov_b32_e32 v25, v2
	v_mov_b32_e32 v26, v2
	v_mov_b32_e32 v27, v2
	v_mov_b32_e32 v28, v2
	v_mov_b32_e32 v29, v2
	v_mov_b32_e32 v30, v2
	v_mov_b32_e32 v31, v2
	v_mov_b32_e32 v32, v2
	v_mov_b32_e32 v33, v2
	s_waitcnt vmcnt(3)
	v_mov_b64_e32 v[84:85], v[36:37]
	s_waitcnt vmcnt(2)
	v_mov_b64_e32 v[88:89], v[52:53]
	s_waitcnt vmcnt(1)
	v_mov_b64_e32 v[92:93], v[56:57]
	s_waitcnt vmcnt(0)
	v_mov_b64_e32 v[96:97], v[60:61]
	v_mov_b64_e32 v[82:83], v[34:35]
	v_mov_b64_e32 v[86:87], v[50:51]
	v_mov_b64_e32 v[90:91], v[54:55]
	v_mov_b64_e32 v[94:95], v[58:59]
	.p2align 6

; __device__ __forceinline__ float bf2f(bf16_t b) { return __uint_as_float(((unsigned)b) << 16); }
; __device__ __forceinline__ void nsa_unit(const Params& p, int bg, int jq, LAS unsigned char* lds, int wave, int lane, bool build_lut) {
;     ...
;             const int cnt = grp ? cntB : cntA, lbase = grp * 64;
;             const int tqg = tq0 + 4 * grp + q4, tq0g = tq0 + 4 * grp;
;             long q8[2];
;             bf16x8 qv2[2];
;             {
;                 const bf16_t* qp = qb + ((size_t)b * S + tqg) * 512 + (g * 4 + r16) * 64 + 8 * fq;
;                 qv2[0] = *(const bf16x8*)(qp); qv2[1] = *(const bf16x8*)(qp + 32);
;             }
;             float m = -1e30f;
;             f32x4 lacc = (f32x4){0.f, 0.f, 0.f, 0.f};
;             const long ones8 = 0x3838383838383838L;
;             f32x4 o[4];
; #pragma unroll
;             for (int dt = 0; dt < 4; ++dt) o[dt] = (f32x4){0.f, 0.f, 0.f, 0.f};
;             const int npair = (cnt + 1) >> 1;
;             if (lane == 0 && (cnt & 1)) list[lbase + cnt] = 0;
;             asm volatile("s_waitcnt lgkmcnt(0)" ::: "memory");
;             __builtin_amdgcn_wave_barrier();
;             long k8[2][8], v8[2][8];
;             int n0 = __builtin_amdgcn_readfirstlane(list[lbase]), n1 = __builtin_amdgcn_readfirstlane(list[lbase + 1]);
; #pragma unroll
;             for (int i = 0; i < 4; ++i) { const l64x2 t0 = *(const l64x2*)(ks8 + (size_t)n0 * 4096 + i * 1024 + lane * 16), t1 = *(const l64x2*)(ks8 + (size_t)n1 * 4096 + i * 1024 + lane * 16);
;                 k8[0][2 * i] = t0[0]; k8[0][2 * i + 1] = t0[1]; k8[1][2 * i] = t1[0]; k8[1][2 * i + 1] = t1[1]; }
; #pragma unroll
;             for (int ks = 0; ks < 2; ++ks) {
;                 float f[8];
; #pragma unroll
;                 for (int e = 0; e < 8; ++e) f[e] = bf2f((bf16_t)qv2[ks][e]) * 4.0f;
;                 q8[ks] = pack_fp8x8(f[0], f[1], f[2], f[3], f[4], f[5], f[6], f[7]);
;             }
.LBB0_1198:
	s_or_b64 exec, exec, s[4:5]
	s_lshl_b32 s4, s8, 2
	s_add_i32 s4, s34, s4
	v_mov_b32_e32 v1, s4
	s_waitcnt lgkmcnt(0)
	ds_read_b64 v[4:5], v1 offset:10560
	s_cmp_lg_u32 s38, 0
	v_or_b32_e32 v165, s7, v160
	s_waitcnt lgkmcnt(0)
	v_readfirstlane_b32 s22, v4
	v_readfirstlane_b32 s8, v5
	s_cbranch_scc0 .LBB0_1279
	s_ashr_i32 s9, s8, 31
	s_lshl_b64 s[4:5], s[8:9], 12
	s_ashr_i32 s23, s22, 31
	v_lshl_add_u64 v[4:5], v[148:149], 0, s[4:5]
	s_lshl_b64 s[4:5], s[22:23], 12
	v_lshl_add_u64 v[16:17], v[148:149], 0, s[4:5]
	global_load_dwordx4 v[32:35], v[4:5], off offset:3072
	global_load_dwordx4 v[8:11], v[4:5], off offset:2048
	global_load_dwordx4 v[36:39], v[16:17], off offset:3072
	global_load_dwordx4 v[20:23], v[16:17], off offset:2048
	global_load_dwordx4 v[12:15], v[4:5], off offset:1024
	s_nop 0
	global_load_dwordx4 v[4:7], v[4:5], off
	s_nop 0
	global_load_dwordx4 v[28:31], v[16:17], off offset:1024
	s_nop 0
	global_load_dwordx4 v[16:19], v[16:17], off
	s_waitcnt vmcnt(9)
	v_lshlrev_b32_e32 v1, 16, v40
	v_and_b32_e32 v3, 0xffff0000, v40
	v_lshlrev_b32_e32 v44, 16, v42
	v_and_b32_e32 v42, 0xffff0000, v42
	v_mul_f32_e32 v1, 4.0, v1
	v_mul_f32_e32 v3, 4.0, v3
	v_mul_f32_e32 v44, 4.0, v44
	v_mul_f32_e32 v42, 4.0, v42
	v_mov_b32_e32 v152, 0
	v_mov_b32_e32 v153, 0
	v_cvt_pk_fp8_f32 v152, v1, v3
	v_cvt_pk_fp8_f32 v153, v44, v42
	v_lshlrev_b32_e32 v40, 16, v41
	v_and_b32_e32 v41, 0xffff0000, v41
	v_lshlrev_b32_e32 v45, 16, v43
	v_and_b32_e32 v1, 0xffff0000, v43
	v_mul_f32_e32 v40, 4.0, v40
	v_mul_f32_e32 v41, 4.0, v41
	v_mul_f32_e32 v45, 4.0, v45
	v_mul_f32_e32 v1, 4.0, v1
	v_cvt_pk_fp8_f32 v152, v40, v41 op_sel:[0,0,1]
	v_cvt_pk_fp8_f32 v153, v45, v1 op_sel:[0,0,1]
	s_waitcnt vmcnt(8)
	v_lshlrev_b32_e32 v1, 16, v24
	v_and_b32_e32 v3, 0xffff0000, v24
	v_lshlrev_b32_e32 v40, 16, v26
	v_and_b32_e32 v26, 0xffff0000, v26
	v_mul_f32_e32 v1, 4.0, v1
	v_mul_f32_e32 v3, 4.0, v3
	v_mul_f32_e32 v40, 4.0, v40
	v_mul_f32_e32 v26, 4.0, v26
	v_mov_b32_e32 v154, 0
	v_mov_b32_e32 v155, 0
	v_cvt_pk_fp8_f32 v154, v1, v3
	v_cvt_pk_fp8_f32 v155, v40, v26
	v_lshlrev_b32_e32 v24, 16, v25
	v_and_b32_e32 v25, 0xffff0000, v25
	v_lshlrev_b32_e32 v41, 16, v27
	v_and_b32_e32 v1, 0xffff0000, v27
	v_mul_f32_e32 v24, 4.0, v24
	v_mul_f32_e32 v25, 4.0, v25
	v_mul_f32_e32 v41, 4.0, v41
	v_mul_f32_e32 v1, 4.0, v1
	v_cvt_pk_fp8_f32 v154, v24, v25 op_sel:[0,0,1]
	v_cvt_pk_fp8_f32 v155, v41, v1 op_sel:[0,0,1]
	s_add_i32 s4, s38, 1
	v_sub_u32_e32 v168, v2, v163
	v_add_u32_e32 v169, v2, v164
	v_mov_b32_e32 v2, v0
	v_mov_b32_e32 v3, v0
	s_lshr_b32 s41, s4, 1
	v_or_b32_e32 v166, s7, v160
	s_lshl_b32 s4, s6, 8
	v_mov_b32_e32 v1, v0
	v_mov_b64_e32 v[26:27], v[2:3]
	v_mov_b64_e32 v[42:43], v[2:3]
	v_mov_b64_e32 v[46:47], v[2:3]
	v_mov_b64_e32 v[50:51], v[2:3]
	v_mov_b64_e32 v[54:55], v[2:3]
	s_mov_b32 s40, 1
	v_lshl_add_u32 v167, v166, 5, s34
	s_max_u32 s42, s41, 1
	v_add_u32_e32 v170, -2, v168
	v_add_u32_e32 v171, -3, v168
	v_add_u32_e32 v172, -16, v168
	v_subrev_u32_e32 v173, 17, v168
	v_subrev_u32_e32 v174, 18, v168
	v_subrev_u32_e32 v175, 19, v168
	v_subrev_u32_e32 v176, 32, v168
	v_subrev_u32_e32 v185, 33, v168
	v_subrev_u32_e32 v186, 34, v168
	v_subrev_u32_e32 v187, 35, v168
	v_subrev_u32_e32 v188, 48, v168
	v_subrev_u32_e32 v189, 49, v168
	v_subrev_u32_e32 v190, 50, v168
	v_subrev_u32_e32 v191, 51, v168
	s_add_i32 s43, s37, s4
	v_mov_b32_e32 v157, 0xf149f2ca
	v_mov_b32_e32 v242, 0x38383838
	v_mov_b32_e32 v243, 0x38383838
	s_mov_b32 s44, 0
	v_mov_b64_e32 v[24:25], v[0:1]
	v_mov_b64_e32 v[40:41], v[0:1]
	v_mov_b64_e32 v[44:45], v[0:1]
	v_mov_b64_e32 v[48:49], v[0:1]
	v_mov_b64_e32 v[52:53], v[0:1]
	.p2align 6

; #define LAS __attribute__((address_space(3)))
; __device__ __forceinline__ void nsa_unit(const Params& p, int bg, int jq, LAS unsigned char* lds, int wave, int lane, bool build_lut) {
;     ...
;         asm volatile("s_waitcnt lgkmcnt(0)" ::: "memory");
;         __builtin_amdgcn_wave_barrier();
;         {
;             const LAS float* park = (const LAS float*)(lds + wave * NSA_WAVE_LDS + 11264);
; #pragma unroll
;             for (int i = 0; i < 16; ++i) { oa0[i] = park[i * 64 + lane]; oa1[i] = park[(16 + i) * 64 + lane]; }
;         }
; #pragma unroll
;         for (int dt = 0; dt < 2; ++dt)
; #pragma unroll
;             for (int i4 = 0; i4 < 4; ++i4) {
;                 const f32x4 v = *(const LAS f32x4*)(ostage + (ql * 4 + r) * 64 + 32 * dt + 8 * i4 + 4 * h);
;                 if (dt == 0) { oa0[4 * i4] += g1 * v[0]; oa0[4 * i4 + 1] += g1 * v[1]; oa0[4 * i4 + 2] += g1 * v[2]; oa0[4 * i4 + 3] += g1 * v[3]; }
;                 else         { oa1[4 * i4] += g1 * v[0]; oa1[4 * i4 + 1] += g1 * v[1]; oa1[4 * i4 + 2] += g1 * v[2]; oa1[4 * i4 + 3] += g1 * v[3]; }
;             }
;         asm volatile("s_waitcnt lgkmcnt(0)" ::: "memory");
;         __builtin_amdgcn_wave_barrier();
;     }
;     {
;         {
;             const bf16_t* qp = qb + tok * 512 + (g * 4 + r) * 64 + h * 8;
;             asm volatile("" : "+v"(qp));
; #pragma unroll
;             for (int ks = 0; ks < 4; ++ks) qf[ks] = *(const bf16x8*)(qp + ks * 16);
;         }
;         const int T0 = max(0, (tq0 - 511) >> 5), T1 = (tq0 + 7) >> 5;
;         float m = -1e30f, l = 0.f;
;         f32x16 o0, o1;
; #pragma unroll
;         for (int i = 0; i < 16; ++i) { o0[i] = 0.f; o1[i] = 0.f; }
;         load_k(kn, kwb + (size_t)(32 * T0) * 64, lane);
;         for (int T = T0; T <= T1; ++T) {
; #pragma unroll
;             for (int ks = 0; ks < 4; ++ks) kf[ks] = kn[ks];
;             load_v(vf, vwT + (size_t)T * 2048, lane);
;             if (T < T1) load_k(kn, kwb + (size_t)(32 * (T + 1)) * 64, lane);
.LBB0_1280:
	v_lshlrev_b32_e32 v1, 8, v145
	v_and_b32_e32 v1, 0x1f00, v1
	v_lshlrev_b32_e32 v2, 4, v179
	v_add3_u32 v1, s34, v1, v2
	s_waitcnt lgkmcnt(0)
	ds_read2st64_b32 v[216:217], v159 offset0:60 offset1:61
	ds_read2st64_b32 v[212:213], v159 offset0:62 offset1:63
	ds_read2st64_b32 v[208:209], v159 offset0:64 offset1:65
	ds_read2st64_b32 v[204:205], v159 offset0:66 offset1:67
	ds_read2st64_b32 v[200:201], v159 offset0:68 offset1:69
	ds_read2st64_b32 v[196:197], v159 offset0:70 offset1:71
	ds_read2st64_b32 v[192:193], v159 offset0:72 offset1:73
	ds_read2st64_b32 v[186:187], v159 offset0:74 offset1:75
	ds_read_b128 v[120:123], v1
	ds_read_b128 v[112:115], v1 offset:32
	ds_read2st64_b32 v[218:219], v159 offset0:44 offset1:45
	ds_read2st64_b32 v[214:215], v159 offset0:46 offset1:47
	ds_read2st64_b32 v[210:211], v159 offset0:48 offset1:49
	ds_read2st64_b32 v[206:207], v159 offset0:50 offset1:51
	ds_read2st64_b32 v[202:203], v159 offset0:52 offset1:53
	ds_read2st64_b32 v[198:199], v159 offset0:54 offset1:55
	ds_read2st64_b32 v[194:195], v159 offset0:56 offset1:57
	ds_read2st64_b32 v[190:191], v159 offset0:58 offset1:59
	ds_read_b128 v[108:111], v1 offset:64
	ds_read_b128 v[100:103], v1 offset:96
	ds_read_b128 v[124:127], v1 offset:128
	ds_read_b128 v[116:119], v1 offset:160
	ds_read_b128 v[104:107], v1 offset:192
	ds_read_b128 v[96:99], v1 offset:224
	s_add_i32 s4, s31, 0xfffffe01
	s_waitcnt lgkmcnt(0)
	v_lshlrev_b32_e32 v188, 1, v144
	v_mov_b32_e32 v189, v0
	s_ashr_i32 s4, s4, 5
	v_lshl_add_u64 v[2:3], v[140:141], 0, v[188:189]
	s_max_i32 s4, s4, 0
	s_ashr_i32 s12, s31, 5
	v_lshl_add_u64 v[2:3], v[142:143], 1, v[2:3]
	s_cmp_le_i32 s4, s12
	s_mov_b64 s[6:7], -1
	s_cbranch_scc0 .LBB0_1327
	v_readlane_b32 s5, v253, 19
	s_lshl_b32 s5, s5, 1
	s_add_u32 s5, s14, s5
	s_addc_u32 s7, s15, 0
	s_add_u32 s6, s5, 0x12b00000
	s_addc_u32 s7, s7, 0
	s_lshl_b32 s8, s4, 5
	s_mov_b32 s9, s72
	v_lshlrev_b32_e32 v4, 3, v145
	s_lshl_b64 s[10:11], s[8:9], 7
	v_ashrrev_i32_e32 v5, 31, v4
	s_add_u32 s10, s6, s10
	v_lshlrev_b64 v[52:53], 1, v[4:5]
	s_addc_u32 s11, s7, s11
	v_lshl_add_u64 v[4:5], s[10:11], 0, v[52:53]
	global_load_dwordx4 v[164:167], v[4:5], off offset:3072
	global_load_dwordx4 v[168:171], v[4:5], off offset:2048
	global_load_dwordx4 v[172:175], v[4:5], off offset:1024
	global_load_dwordx4 v[48:51], v[4:5], off
	flat_load_dwordx4 v[128:131], v[2:3] offset:96
	flat_load_dwordx4 v[132:135], v[2:3] offset:64
	flat_load_dwordx4 v[136:139], v[2:3] offset:32
	flat_load_dwordx4 v[140:143], v[2:3]
	v_mov_b32_e32 v14, v0
	v_mov_b32_e32 v15, v0
	v_mov_b32_e32 v1, v0
	v_mov_b32_e32 v2, v0
	v_mov_b32_e32 v3, v0
	v_mov_b32_e32 v4, v0
	v_mov_b32_e32 v5, v0
	v_mov_b32_e32 v6, v0
	v_mov_b32_e32 v7, v0
	v_mov_b32_e32 v8, v0
	v_mov_b32_e32 v9, v0
	v_mov_b32_e32 v10, v0
	v_mov_b32_e32 v11, v0
	v_mov_b32_e32 v12, v0
	v_mov_b32_e32 v13, v0
	v_mov_b64_e32 v[30:31], v[14:15]
	v_mov_b64_e32 v[46:47], v[14:15]
	v_mov_b64_e32 v[28:29], v[12:13]
	v_mov_b64_e32 v[26:27], v[10:11]
	v_mov_b64_e32 v[24:25], v[8:9]
	v_mov_b64_e32 v[22:23], v[6:7]
	v_mov_b64_e32 v[20:21], v[4:5]
	v_mov_b64_e32 v[18:19], v[2:3]
	v_mov_b64_e32 v[16:17], v[0:1]
	v_mov_b64_e32 v[44:45], v[12:13]
	v_mov_b64_e32 v[42:43], v[10:11]
	v_mov_b64_e32 v[40:41], v[8:9]
	v_mov_b64_e32 v[38:39], v[6:7]
	v_mov_b64_e32 v[36:37], v[4:5]
	v_mov_b64_e32 v[34:35], v[2:3]
	v_mov_b64_e32 v[32:33], v[0:1]
	v_lshl_add_u64 v[14:15], s[6:7], 0, v[52:53]
	s_lshl_b32 s7, s29, 6
	s_add_i32 s7, s28, s7
	s_add_i32 s7, s7, s30
	s_sub_i32 s7, s7, s8
	s_add_i32 s6, s8, 32
	s_add_i32 s13, s7, 7
	v_readlane_b32 s7, v253, 54
	s_mov_b32 s5, s72
	s_add_u32 s7, s14, s7
	v_readlane_b32 s8, v253, 55
	s_addc_u32 s10, s15, s8
	s_lshl_b64 s[8:9], s[4:5], 12
	s_add_u32 s8, s7, s8
	v_lshlrev_b32_e32 v176, 2, v179
	s_addc_u32 s9, s10, s9
	v_mov_b32_e32 v185, 0xf149f2ca
	v_mov_b32_e32 v189, 0
	v_sub_u32_e32 v180, v158, v176
	v_lshl_add_u64 v[220:221], s[8:9], 0, v[52:53]
	s_waitcnt vmcnt(0)
	v_mov_b64_e32 v[144:145], v[164:165]
	v_mov_b64_e32 v[10:11], v[168:169]
	v_mov_b64_e32 v[6:7], v[172:173]
	v_mov_b64_e32 v[2:3], v[48:49]
	v_mov_b64_e32 v[4:5], v[50:51]
	v_mov_b64_e32 v[8:9], v[174:175]
	v_mov_b64_e32 v[12:13], v[170:171]
	v_mov_b64_e32 v[146:147], v[166:167]
	.p2align 6

; template <class Epi>
; __device__ __forceinline__ void gemm_phase(LAS unsigned char* lds, const Gemm g, const StaticOrder& S, const Epi& E) {
;     ...
;         const bool has_next = S.next(ui + 1, nxt);
;         const char* nA = has_next ? (const char*)g.A + (size_t)nxt.pm * tA : cA; const char* nB = has_next ? (const char*)g.Bt + (size_t)nxt.pn * tB : cB;
;         for (int t = 0; t < nt; t += 2) {
;     ...
; #pragma unroll
;         for (int a = 0; a < 2; ++a)
; #pragma unroll
;             for (int b = 0; b < 2; ++b)
; #pragma unroll
;                 for (int m = 0; m < 4; ++m)
; #pragma unroll
;                     for (int n = 0; n < 2; ++n) acc[a][b][m][n] = (f32x4){0.f, 0.f, 0.f, 0.f};
;         cur = nxt; cA = nA; cB = nB; ++ui;
.LBB0_1397:
	s_ashr_i32 s35, s34, 31
	s_lshl_b64 s[36:37], s[34:35], 19
	s_add_u32 s27, s46, s36
	s_addc_u32 s29, s47, s37
	s_and_b64 s[36:37], s[38:39], exec
	s_cselect_b32 s37, s29, s9
	s_cselect_b32 s36, s27, s8
	s_ashr_i32 s31, s30, 31
	s_lshl_b64 s[40:41], s[30:31], 19
	s_add_u32 s27, s48, s40
	s_addc_u32 s29, s49, s41
	s_and_b64 s[38:39], s[38:39], exec
	s_cselect_b32 s39, s29, s11
	s_cselect_b32 s38, s27, s10
	s_add_u32 s8, s8, 0x40080
	s_addc_u32 s9, s9, 0
	s_add_u32 s27, s10, 0x100
	v_mov_b64_e32 v[2:3], 0
	v_mov_b64_e32 v[4:5], 0
	v_mov_b64_e32 v[6:7], 0
	v_mov_b64_e32 v[8:9], 0
	v_mov_b64_e32 v[10:11], 0
	v_mov_b64_e32 v[12:13], 0
	v_mov_b64_e32 v[14:15], 0
	v_mov_b64_e32 v[16:17], 0
	v_mov_b64_e32 v[18:19], 0
	v_mov_b64_e32 v[20:21], 0
	v_mov_b64_e32 v[22:23], 0
	v_mov_b64_e32 v[24:25], 0
	v_mov_b64_e32 v[26:27], 0
	v_mov_b64_e32 v[28:29], 0
	v_mov_b64_e32 v[30:31], 0
	v_mov_b64_e32 v[32:33], 0
	v_mov_b64_e32 v[34:35], 0
	v_mov_b64_e32 v[36:37], 0
	v_mov_b64_e32 v[38:39], 0
	v_mov_b64_e32 v[40:41], 0
	v_mov_b64_e32 v[42:43], 0
	v_mov_b64_e32 v[44:45], 0
	v_mov_b64_e32 v[46:47], 0
	v_mov_b64_e32 v[48:49], 0
	v_mov_b64_e32 v[50:51], 0
	v_mov_b64_e32 v[52:53], 0
	v_mov_b64_e32 v[54:55], 0
	v_mov_b64_e32 v[56:57], 0
	v_mov_b64_e32 v[58:59], 0
	v_mov_b64_e32 v[60:61], 0
	v_mov_b64_e32 v[62:63], 0
	v_mov_b64_e32 v[64:65], 0
	v_mov_b64_e32 v[66:67], 0
	v_mov_b64_e32 v[68:69], 0
	v_mov_b64_e32 v[70:71], 0
	v_mov_b64_e32 v[72:73], 0
	v_mov_b64_e32 v[74:75], 0
	v_mov_b64_e32 v[76:77], 0
	v_mov_b64_e32 v[78:79], 0
	v_mov_b64_e32 v[80:81], 0
	v_mov_b64_e32 v[82:83], 0
	v_mov_b64_e32 v[84:85], 0
	v_mov_b64_e32 v[86:87], 0
	v_mov_b64_e32 v[88:89], 0
	v_mov_b64_e32 v[90:91], 0
	v_mov_b64_e32 v[92:93], 0
	v_mov_b64_e32 v[94:95], 0
	v_mov_b64_e32 v[96:97], 0
	v_mov_b64_e32 v[98:99], 0
	v_mov_b64_e32 v[100:101], 0
	v_mov_b64_e32 v[102:103], 0
	v_mov_b64_e32 v[104:105], 0
	v_mov_b64_e32 v[106:107], 0
	v_mov_b64_e32 v[108:109], 0
	v_mov_b64_e32 v[110:111], 0
	v_mov_b64_e32 v[112:113], 0
	v_mov_b64_e32 v[114:115], 0
	v_mov_b64_e32 v[116:117], 0
	v_mov_b64_e32 v[118:119], 0
	v_mov_b64_e32 v[120:121], 0
	v_mov_b64_e32 v[122:123], 0
	v_mov_b64_e32 v[124:125], 0
	v_mov_b64_e32 v[126:127], 0
	v_mov_b64_e32 v[128:129], 0
	s_addc_u32 s29, s11, 0
	s_mov_b32 s31, -2
	s_waitcnt lgkmcnt(0)
	.p2align 6

; template <class Epi>
; __device__ __forceinline__ void gemm_phase(LAS unsigned char* lds, const Gemm g, const StaticOrder& S, const Epi& E) {
;     ...
;         const bool has_next = S.next(ui + 1, nxt);
;         const char* nA = has_next ? (const char*)g.A + (size_t)nxt.pm * tA : cA; const char* nB = has_next ? (const char*)g.Bt + (size_t)nxt.pn * tB : cB;
;         for (int t = 0; t < nt; t += 2) {
;     ...
; #pragma unroll
;         for (int a = 0; a < 2; ++a)
; #pragma unroll
;             for (int b = 0; b < 2; ++b)
; #pragma unroll
;                 for (int m = 0; m < 4; ++m)
; #pragma unroll
;                     for (int n = 0; n < 2; ++n) acc[a][b][m][n] = (f32x4){0.f, 0.f, 0.f, 0.f};
;         cur = nxt; cA = nA; cB = nB; ++ui;
.LBB0_1549:
	s_ashr_i32 s15, s14, 31
	s_lshl_b64 s[16:17], s[14:15], 19
	s_add_u32 s16, s27, s16
	s_addc_u32 s17, s28, s17
	s_and_b64 s[18:19], s[24:25], exec
	s_cselect_b32 s15, s17, s21
	s_cselect_b32 s46, s16, s20
	s_ashr_i32 s13, s12, 31
	s_lshl_b64 s[18:19], s[12:13], 19
	s_add_u32 s18, s29, s18
	s_addc_u32 s19, s30, s19
	s_and_b64 s[24:25], s[24:25], exec
	s_cselect_b32 s13, s19, s23
	s_cselect_b32 s47, s18, s22
	s_add_u32 s20, s20, 0x40080
	s_addc_u32 s21, s21, 0
	s_add_u32 s48, s22, 0x100
	v_mov_b64_e32 v[2:3], 0
	v_mov_b64_e32 v[4:5], 0
	v_mov_b64_e32 v[6:7], 0
	v_mov_b64_e32 v[8:9], 0
	v_mov_b64_e32 v[10:11], 0
	v_mov_b64_e32 v[12:13], 0
	v_mov_b64_e32 v[14:15], 0
	v_mov_b64_e32 v[16:17], 0
	v_mov_b64_e32 v[18:19], 0
	v_mov_b64_e32 v[20:21], 0
	v_mov_b64_e32 v[22:23], 0
	v_mov_b64_e32 v[24:25], 0
	v_mov_b64_e32 v[26:27], 0
	v_mov_b64_e32 v[28:29], 0
	v_mov_b64_e32 v[30:31], 0
	v_mov_b64_e32 v[32:33], 0
	v_mov_b64_e32 v[34:35], 0
	v_mov_b64_e32 v[36:37], 0
	v_mov_b64_e32 v[38:39], 0
	v_mov_b64_e32 v[40:41], 0
	v_mov_b64_e32 v[42:43], 0
	v_mov_b64_e32 v[44:45], 0
	v_mov_b64_e32 v[46:47], 0
	v_mov_b64_e32 v[48:49], 0
	v_mov_b64_e32 v[50:51], 0
	v_mov_b64_e32 v[52:53], 0
	v_mov_b64_e32 v[54:55], 0
	v_mov_b64_e32 v[56:57], 0
	v_mov_b64_e32 v[58:59], 0
	v_mov_b64_e32 v[60:61], 0
	v_mov_b64_e32 v[62:63], 0
	v_mov_b64_e32 v[64:65], 0
	v_mov_b64_e32 v[66:67], 0
	v_mov_b64_e32 v[68:69], 0
	v_mov_b64_e32 v[70:71], 0
	v_mov_b64_e32 v[72:73], 0
	v_mov_b64_e32 v[74:75], 0
	v_mov_b64_e32 v[76:77], 0
	v_mov_b64_e32 v[78:79], 0
	v_mov_b64_e32 v[80:81], 0
	v_mov_b64_e32 v[82:83], 0
	v_mov_b64_e32 v[84:85], 0
	v_mov_b64_e32 v[86:87], 0
	v_mov_b64_e32 v[88:89], 0
	v_mov_b64_e32 v[90:91], 0
	v_mov_b64_e32 v[92:93], 0
	v_mov_b64_e32 v[94:95], 0
	v_mov_b64_e32 v[96:97], 0
	v_mov_b64_e32 v[98:99], 0
	v_mov_b64_e32 v[100:101], 0
	v_mov_b64_e32 v[102:103], 0
	v_mov_b64_e32 v[104:105], 0
	v_mov_b64_e32 v[106:107], 0
	v_mov_b64_e32 v[108:109], 0
	v_mov_b64_e32 v[110:111], 0
	v_mov_b64_e32 v[112:113], 0
	v_mov_b64_e32 v[114:115], 0
	v_mov_b64_e32 v[116:117], 0
	v_mov_b64_e32 v[118:119], 0
	v_mov_b64_e32 v[120:121], 0
	v_mov_b64_e32 v[122:123], 0
	v_mov_b64_e32 v[124:125], 0
	v_mov_b64_e32 v[126:127], 0
	v_mov_b64_e32 v[128:129], 0
	s_addc_u32 s49, s23, 0
	s_mov_b32 s50, -2
	.p2align 6

; template <class Epi>
; __device__ __forceinline__ void gemm_phase(LAS unsigned char* lds, const Gemm g, const StaticOrder& S, const Epi& E) {
;     ...
; #pragma unroll
;         for (int a = 0; a < 2; ++a)
; #pragma unroll
;             for (int b = 0; b < 2; ++b)
; #pragma unroll
;                 for (int m = 0; m < 4; ++m)
; #pragma unroll
;                     for (int n = 0; n < 2; ++n) acc[a][b][m][n] = (f32x4){0.f, 0.f, 0.f, 0.f};
;         cur = nxt; cA = nA; cB = nB; ++ui;
.LBB0_1631:
	s_add_u32 s35, s42, 0x100
	v_mov_b64_e32 v[2:3], 0
	v_mov_b64_e32 v[4:5], 0
	v_mov_b64_e32 v[6:7], 0
	v_mov_b64_e32 v[8:9], 0
	v_mov_b64_e32 v[10:11], 0
	v_mov_b64_e32 v[12:13], 0
	v_mov_b64_e32 v[14:15], 0
	v_mov_b64_e32 v[16:17], 0
	v_mov_b64_e32 v[18:19], 0
	v_mov_b64_e32 v[20:21], 0
	v_mov_b64_e32 v[22:23], 0
	v_mov_b64_e32 v[24:25], 0
	v_mov_b64_e32 v[26:27], 0
	v_mov_b64_e32 v[28:29], 0
	v_mov_b64_e32 v[30:31], 0
	v_mov_b64_e32 v[32:33], 0
	v_mov_b64_e32 v[34:35], 0
	v_mov_b64_e32 v[36:37], 0
	v_mov_b64_e32 v[38:39], 0
	v_mov_b64_e32 v[40:41], 0
	v_mov_b64_e32 v[42:43], 0
	v_mov_b64_e32 v[44:45], 0
	v_mov_b64_e32 v[46:47], 0
	v_mov_b64_e32 v[48:49], 0
	v_mov_b64_e32 v[50:51], 0
	v_mov_b64_e32 v[52:53], 0
	v_mov_b64_e32 v[54:55], 0
	v_mov_b64_e32 v[56:57], 0
	v_mov_b64_e32 v[58:59], 0
	v_mov_b64_e32 v[60:61], 0
	v_mov_b64_e32 v[62:63], 0
	v_mov_b64_e32 v[64:65], 0
	v_mov_b64_e32 v[66:67], 0
	v_mov_b64_e32 v[68:69], 0
	v_mov_b64_e32 v[70:71], 0
	v_mov_b64_e32 v[72:73], 0
	v_mov_b64_e32 v[74:75], 0
	v_mov_b64_e32 v[76:77], 0
	v_mov_b64_e32 v[78:79], 0
	v_mov_b64_e32 v[80:81], 0
	v_mov_b64_e32 v[82:83], 0
	v_mov_b64_e32 v[84:85], 0
	v_mov_b64_e32 v[86:87], 0
	v_mov_b64_e32 v[88:89], 0
	v_mov_b64_e32 v[90:91], 0
	v_mov_b64_e32 v[92:93], 0
	v_mov_b64_e32 v[94:95], 0
	v_mov_b64_e32 v[96:97], 0
	v_mov_b64_e32 v[98:99], 0
	v_mov_b64_e32 v[100:101], 0
	v_mov_b64_e32 v[102:103], 0
	v_mov_b64_e32 v[104:105], 0
	v_mov_b64_e32 v[106:107], 0
	v_mov_b64_e32 v[108:109], 0
	v_mov_b64_e32 v[110:111], 0
	v_mov_b64_e32 v[112:113], 0
	v_mov_b64_e32 v[114:115], 0
	v_mov_b64_e32 v[116:117], 0
	v_mov_b64_e32 v[118:119], 0
	v_mov_b64_e32 v[120:121], 0
	v_mov_b64_e32 v[122:123], 0
	v_mov_b64_e32 v[124:125], 0
	v_mov_b64_e32 v[126:127], 0
	v_mov_b64_e32 v[128:129], 0
	s_addc_u32 s37, s43, 0
	s_mov_b32 s67, -2
	.p2align 6
